# attention row-max exchange via v_permlane32_swap instead of ds_bpermute
# speedup vs baseline: 1.0338x; 1.0031x over previous
.LBB0_270:
	v_max_f32_e32 v48, v33, v33
	v_max_f32_e32 v49, v32, v32
	v_max_f32_e32 v48, v49, v48
	v_max3_f32 v48, v48, v34, v35
	v_max3_f32 v48, v48, v36, v37
	v_max3_f32 v48, v48, v38, v39
	v_max3_f32 v48, v48, v40, v41
	v_xor_b32_e32 v49, 32, v236
	v_add_u32_e32 v50, 64, v237
	v_max3_f32 v48, v48, v42, v43
	v_cmp_lt_i32_e32 vcc, v49, v50
	v_max3_f32 v48, v48, v44, v45
	v_max3_f32 v48, v48, v46, v47
	v_cndmask_b32_e32 v49, v236, v49, vcc
	v_lshlrev_b32_e32 v189, 2, v49
	v_mov_b32_e32 v49, v48
	v_mov_b32_e32 v50, v48
	s_nop 1
	v_permlane32_swap_b32_e32 v49, v50
	v_max3_f32 v191, v233, v49, v50
	v_add_f32_e32 v48, 0x41000000, v233
	v_cmp_gt_f32_e32 vcc, v191, v48
	s_cbranch_vccnz .Latt_updA
	v_mov_b32_e32 v191, v233
	v_mov_b32_e32 v198, 1.0
	s_branch .LBB0_272

.LBB0_278:
	v_max_f32_e32 v48, v33, v33
	v_max_f32_e32 v49, v32, v32
	v_max_f32_e32 v48, v49, v48
	v_max3_f32 v48, v48, v34, v35
	v_max3_f32 v48, v48, v36, v37
	v_max3_f32 v48, v48, v38, v39
	v_max3_f32 v48, v48, v40, v41
	v_max3_f32 v48, v48, v42, v43
	v_max3_f32 v48, v48, v44, v45
	v_max3_f32 v48, v48, v46, v47
	v_mov_b32_e32 v49, v48
	v_mov_b32_e32 v50, v48
	s_nop 1
	v_permlane32_swap_b32_e32 v49, v50
	v_max3_f32 v233, v191, v49, v50
	v_add_f32_e32 v48, 0x41000000, v191
	v_cmp_gt_f32_e32 vcc, v233, v48
	s_cbranch_vccnz .Latt_updB
	v_mov_b32_e32 v233, v191
	v_mov_b32_e32 v48, 1.0
	s_branch .LBB0_280

.LBB0_280:
	v_sub_f32_e32 v32, v32, v233
	v_exp_f32_e32 v32, v32
	v_sub_f32_e32 v33, v33, v233
	v_exp_f32_e32 v33, v33
	v_sub_f32_e32 v34, v34, v233
	v_exp_f32_e32 v34, v34
	v_sub_f32_e32 v35, v35, v233
	v_sub_f32_e32 v36, v36, v233
	v_sub_f32_e32 v37, v37, v233
	v_sub_f32_e32 v38, v38, v233
	v_sub_f32_e32 v39, v39, v233
	v_exp_f32_e32 v35, v35
	v_exp_f32_e32 v36, v36
	v_exp_f32_e32 v37, v37
	v_exp_f32_e32 v38, v38
	v_exp_f32_e32 v39, v39
	v_add_f32_e32 v50, 0, v32
	v_add_f32_e32 v50, v33, v50
	v_add_f32_e32 v49, 0, v193
	v_add_f32_e32 v50, v34, v50
	v_add_f32_e32 v49, v195, v49
	v_add_f32_e32 v50, v35, v50
	v_cvt_pk_bf16_f32 v32, v32, v33
	v_cvt_pk_bf16_f32 v33, v34, v35
	v_cvt_pk_bf16_f32 v34, v36, v37
	v_cvt_pk_bf16_f32 v35, v38, v39
	v_add_f32_e32 v49, v197, v49
	v_add_f32_e32 v49, v200, v49
	s_waitcnt lgkmcnt(0)
	v_mfma_f32_32x32x16_bf16 v[16:31], v[142:145], v[32:35], v[16:31]
	v_add_f32_e32 v49, v201, v49
	v_sub_f32_e32 v40, v40, v233
	v_sub_f32_e32 v41, v41, v233
	v_sub_f32_e32 v42, v42, v233
	v_sub_f32_e32 v43, v43, v233
	v_sub_f32_e32 v44, v44, v233
	v_sub_f32_e32 v45, v45, v233
	v_mfma_f32_32x32x16_bf16 v[0:15], v[134:137], v[32:35], v[0:15]
	v_sub_f32_e32 v46, v46, v233
	v_sub_f32_e32 v47, v47, v233
	v_add_f32_e32 v49, v202, v49
	v_add_f32_e32 v50, v36, v50
	v_exp_f32_e32 v40, v40
	v_exp_f32_e32 v41, v41
	v_exp_f32_e32 v42, v42
	v_exp_f32_e32 v43, v43
	v_exp_f32_e32 v44, v44
	v_exp_f32_e32 v45, v45
	v_exp_f32_e32 v46, v46
	v_exp_f32_e32 v47, v47
	v_add_f32_e32 v49, v203, v49
	v_add_f32_e32 v50, v37, v50
	v_add_f32_e32 v49, v204, v49
	v_add_f32_e32 v50, v38, v50
	v_add_f32_e32 v49, v205, v49
	v_add_f32_e32 v50, v39, v50
	v_add_f32_e32 v49, v206, v49
	v_add_f32_e32 v50, v40, v50
	v_cvt_pk_bf16_f32 v36, v40, v41
	v_cvt_pk_bf16_f32 v37, v42, v43
	v_cvt_pk_bf16_f32 v38, v44, v45
	v_cvt_pk_bf16_f32 v39, v46, v47
	v_add_f32_e32 v49, v207, v49
	v_add_f32_e32 v50, v41, v50
	v_mfma_f32_32x32x16_bf16 v[16:31], v[138:141], v[36:39], v[16:31]
	v_add_f32_e32 v49, v208, v49
	v_add_f32_e32 v50, v42, v50
	v_add_f32_e32 v49, v209, v49
	v_add_f32_e32 v50, v43, v50
	v_add_f32_e32 v49, v210, v49
	v_add_f32_e32 v50, v44, v50
	v_add_f32_e32 v49, v211, v49
	v_mfma_f32_32x32x16_bf16 v[0:15], v[130:133], v[36:39], v[0:15]
	v_add_f32_e32 v50, v45, v50
	v_add_f32_e32 v49, v212, v49
	v_add_f32_e32 v50, v46, v50
	v_fmac_f32_e32 v49, v251, v198
	v_add_f32_e32 v251, v47, v50
	s_add_i32 s11, s11, 64
	v_fmac_f32_e32 v251, v49, v48
	v_subrev_u32_e32 v247, 64, v247
	s_cmp_gt_u32 s28, 7
	s_cbranch_scc1 .LBB0_282
	s_branch .LBB0_264
